# qk_prep row loop: norm-gain vector hoisted out of the loop (fixed per wave), rope table row loaded at the loop top with the row instead of after the norm
# speedup vs baseline: 1.0052x; 1.0052x over previous
.LBB0_626:
	s_andn2_b64 vcc, exec, s[2:3]
	s_cbranch_vccnz .LBB0_980
	s_and_b64 vcc, exec, s[38:39]
	s_cbranch_vccnz .LBB0_642
	s_load_dwordx4 s[4:7], s[0:1], 0xf8
	s_mov_b32 s2, s86
	s_waitcnt vmcnt(12)
	v_mov_b32_e32 v0, v190
	s_waitcnt lgkmcnt(0)
	s_mov_b64 s[10:11], s[6:7]
	s_nop 0
	v_ashrrev_i32_e32 v1, 6, v0
	v_lshl_add_u32 v41, s2, 3, v1
	s_mov_b32 s2, 0x8800
	v_mov_b32_e32 v1, v190
	v_cmp_gt_i32_e32 vcc, s2, v41
	s_and_saveexec_b64 s[8:9], vcc
	s_cbranch_execz .LBB0_641
	v_and_b32_e32 v3, 7, v1
	v_lshlrev_b32_e32 v160, 5, v3
	s_waitcnt vmcnt(11)
	v_lshl_add_u64 v[4:5], s[10:11], 0, v[160:161]
	s_mov_b64 s[2:3], 0x21344d00
	v_lshl_add_u64 v[32:33], v[4:5], 0, s[2:3]
	v_lshlrev_b32_e32 v4, 6, v1
	v_and_b32_e32 v160, 64, v4
	v_bfe_u32 v2, v1, 3, 3
	v_lshl_add_u64 v[4:5], s[10:11], 0, v[160:161]
	s_mov_b64 s[2:3], 0x32f14d00
	v_and_b32_e32 v1, 2, v1
	v_and_b32_e32 v0, 64, v0
	v_lshl_add_u64 v[34:35], v[4:5], 0, s[2:3]
	v_cmp_eq_u32_e64 s[2:3], 0, v1
	v_cmp_ne_u32_e64 s[4:5], 0, v0
	v_cmp_eq_u32_e64 s[6:7], 0, v0
	v_mov_b32_e32 v0, 0x27e94d00
	v_mov_b32_e32 v1, 0x24b94d00
	v_mul_u32_u24_e32 v6, 0xc0, v2
	v_cndmask_b32_e64 v160, v0, v1, s[6:7]
	v_lshl_add_u64 v[0:1], s[10:11], 0, v[160:161]
	v_lshlrev_b32_e32 v160, 1, v6
	v_lshlrev_b32_e32 v2, 3, v3
	v_lshl_add_u64 v[0:1], v[0:1], 0, v[160:161]
	v_lshlrev_b32_e32 v160, 4, v3
	s_mul_i32 s24, s72, 0xc0
	v_cmp_gt_u32_e32 vcc, 4, v3
	v_lshl_add_u64 v[36:37], v[0:1], 0, v[160:161]
	s_mov_b64 s[10:11], 0
	v_lshlrev_b32_e32 v160, 2, v2
	v_mov_b32_e32 v0, 15
	v_mov_b32_e32 v1, 16
	v_cndmask_b32_e64 v0, v0, v1, s[4:5]
	v_mov_b32_e32 v1, v161
	v_lshl_add_u64 v[0:1], v[0:1], 3, s[0:1]
	global_load_dwordx2 v[8:9], v[0:1], off
	s_waitcnt vmcnt(0)
	v_lshl_add_u64 v[8:9], s[24:25], 2, v[8:9]
	v_lshl_add_u64 v[28:29], v[8:9], 0, v[160:161]
	global_load_dwordx4 v[76:79], v[28:29], off offset:16
	global_load_dwordx4 v[72:75], v[28:29], off
	global_load_dwordx4 v[84:87], v[28:29], off offset:272
	global_load_dwordx4 v[80:83], v[28:29], off offset:256
	global_load_dwordx4 v[92:95], v[28:29], off offset:528
	global_load_dwordx4 v[88:91], v[28:29], off offset:512
	s_waitcnt vmcnt(0)
	s_branch .LBB0_631
.LBB0_630:
	s_or_b64 exec, exec, s[12:13]
	v_mul_f32_e32 v18, v40, v57
	v_mul_f32_e32 v12, v72, v18
	v_mul_f32_e32 v18, v40, v56
	v_mul_f32_e32 v13, v73, v18
	v_mul_f32_e32 v18, v40, v55
	v_mul_f32_e32 v14, v74, v18
	v_mul_f32_e32 v18, v40, v54
	v_mul_f32_e32 v15, v75, v18
	v_mul_f32_e32 v18, v40, v53
	v_mul_f32_e32 v8, v76, v18
	v_mul_f32_e32 v18, v40, v52
	v_mul_f32_e32 v9, v77, v18
	v_mul_f32_e32 v18, v40, v51
	v_mul_f32_e32 v10, v78, v18
	v_mul_f32_e32 v18, v40, v50
	v_mul_f32_e32 v11, v79, v18
	v_mul_f32_e32 v18, v40, v49
	v_mul_f32_e32 v4, v80, v18
	v_mul_f32_e32 v18, v40, v48
	v_mul_f32_e32 v5, v81, v18
	v_mul_f32_e32 v18, v40, v47
	v_mul_f32_e32 v6, v82, v18
	v_mul_f32_e32 v18, v40, v46
	v_mul_f32_e32 v7, v83, v18
	v_mul_f32_e32 v18, v40, v45
	v_mul_f32_e32 v18, v84, v18
	v_mul_f32_e32 v0, v40, v44
	v_mul_f32_e32 v19, v85, v0
	v_mul_f32_e32 v0, v40, v43
	v_readlane_b32 s6, v254, 7
	v_mul_f32_e32 v24, v86, v0
	v_mul_f32_e32 v0, v40, v42
	v_readlane_b32 s7, v254, 8
	v_add_u32_e32 v41, s6, v41
	s_mov_b32 s6, 0x87ff
	v_mul_f32_e32 v25, v87, v0
	v_cvt_pk_bf16_f32 v0, v12, v13
	v_cvt_pk_bf16_f32 v1, v14, v15
	v_cvt_pk_bf16_f32 v2, v8, v9
	v_cvt_pk_bf16_f32 v3, v10, v11
	v_cmp_lt_i32_e64 s[6:7], s6, v41
	global_store_dwordx4 v[38:39], v[0:3], off
	s_or_b64 s[10:11], s[6:7], s[10:11]
	s_nop 0
	v_cvt_pk_bf16_f32 v0, v4, v5
	v_cvt_pk_bf16_f32 v1, v6, v7
	v_cvt_pk_bf16_f32 v2, v18, v19
	v_cvt_pk_bf16_f32 v3, v24, v25
	global_store_dwordx4 v[38:39], v[0:3], off offset:128
	s_nop 1
	v_cvt_pk_bf16_f32 v0, v20, v21
	v_cvt_pk_bf16_f32 v1, v28, v29
	v_cvt_pk_bf16_f32 v2, v22, v23
	v_cvt_pk_bf16_f32 v3, v16, v17
	global_store_dwordx4 v[38:39], v[0:3], off offset:256
	s_andn2_b64 exec, exec, s[10:11]
	s_cbranch_execz .LBB0_641
.LBB0_631:
	v_ashrrev_i32_e32 v59, 1, v41
	s_movk_i32 s6, 0xc00
	v_mad_i64_i32 v[38:39], s[6:7], v59, s6, v[36:37]
	v_lshrrev_b32_e32 v18, 6, v59
	v_cndmask_b32_e32 v18, v59, v18, vcc
	v_lshlrev_b32_e32 v18, 7, v18
	v_and_b32_e32 v18, 0x1f80, v18
	v_mov_b32_e32 v19, v161
	v_lshl_add_u64 v[18:19], v[34:35], 0, v[18:19]
	global_load_dwordx4 v[24:27], v[18:19], off offset:48
	global_load_dwordx4 v[60:63], v[18:19], off offset:32
	global_load_dwordx4 v[64:67], v[18:19], off offset:16
	global_load_dwordx4 v[68:71], v[18:19], off
	global_load_dwordx4 v[4:7], v[38:39], off
	s_nop 0
	global_load_dwordx4 v[0:3], v[38:39], off offset:128
	s_and_saveexec_b64 s[6:7], s[4:5]
	s_xor_b64 s[6:7], exec, s[6:7]
	s_cbranch_execz .LBB0_637
	s_movk_i32 s12, 0x140
	s_waitcnt vmcnt(13)
	v_mad_i64_i32 v[10:11], s[12:13], v59, s12, v[32:33]
	global_load_dwordx4 v[16:19], v[10:11], off offset:16
	global_load_dwordx4 v[20:23], v[10:11], off

.LBB0_639:
	s_or_b64 exec, exec, s[6:7]
	s_waitcnt vmcnt(1)
	v_and_b32_e32 v56, 0xffff0000, v4
	v_lshlrev_b32_e32 v57, 16, v4
	s_waitcnt vmcnt(0)
	v_lshlrev_b32_e32 v45, 16, v2
	v_and_b32_e32 v44, 0xffff0000, v2
	v_mul_f32_e32 v2, v56, v56
	v_lshlrev_b32_e32 v55, 16, v5
	v_fmac_f32_e32 v2, v57, v57
	v_and_b32_e32 v54, 0xffff0000, v5
	v_fmac_f32_e32 v2, v55, v55
	v_lshlrev_b32_e32 v53, 16, v6
	v_fmac_f32_e32 v2, v54, v54
	v_and_b32_e32 v52, 0xffff0000, v6
	v_fmac_f32_e32 v2, v53, v53
	v_lshlrev_b32_e32 v51, 16, v7
	v_fmac_f32_e32 v2, v52, v52
	v_and_b32_e32 v50, 0xffff0000, v7
	v_fmac_f32_e32 v2, v51, v51
	v_lshlrev_b32_e32 v49, 16, v0
	v_fmac_f32_e32 v2, v50, v50
	v_and_b32_e32 v48, 0xffff0000, v0
	v_fmac_f32_e32 v2, v49, v49
	v_lshlrev_b32_e32 v47, 16, v1
	v_fmac_f32_e32 v2, v48, v48
	v_and_b32_e32 v46, 0xffff0000, v1
	v_fmac_f32_e32 v2, v47, v47
	v_fmac_f32_e32 v2, v46, v46
	v_fmac_f32_e32 v2, v45, v45
	v_lshlrev_b32_e32 v43, 16, v3
	v_fmac_f32_e32 v2, v44, v44
	v_and_b32_e32 v42, 0xffff0000, v3
	v_fmac_f32_e32 v2, v43, v43
	v_fmac_f32_e32 v2, v42, v42
	v_pk_mul_f32 v[0:1], v[20:21], v[20:21]
	v_add_f32_e32 v0, v2, v0
	v_add_f32_e32 v2, v1, v0
	v_pk_mul_f32 v[0:1], v[22:23], v[22:23]
	v_add_f32_e32 v0, v0, v2
	v_add_f32_e32 v2, v1, v0
	v_pk_mul_f32 v[0:1], v[16:17], v[16:17]
	s_nop 0
	v_add_f32_e32 v0, v0, v2
	v_add_f32_e32 v2, v1, v0
	v_pk_mul_f32 v[0:1], v[18:19], v[18:19]
	s_nop 0
	v_add_f32_e32 v0, v0, v2
	v_and_b32_e32 v2, 64, v227
	v_add_f32_e32 v0, v1, v0
	v_xor_b32_e32 v1, 1, v227
	v_add_u32_e32 v2, 64, v2
	v_cmp_lt_i32_e64 s[6:7], v1, v2
	s_nop 1
	v_cndmask_b32_e64 v1, v227, v1, s[6:7]
	v_lshlrev_b32_e32 v1, 2, v1
	ds_bpermute_b32 v1, v1, v0
	s_waitcnt lgkmcnt(0)
	v_add_f32_e32 v0, v0, v1
	v_xor_b32_e32 v1, 2, v227
	v_cmp_lt_i32_e64 s[6:7], v1, v2
	s_nop 1
	v_cndmask_b32_e64 v1, v227, v1, s[6:7]
	v_lshlrev_b32_e32 v58, 2, v1
	ds_bpermute_b32 v1, v58, v0
	s_waitcnt lgkmcnt(0)
	v_add_f32_e32 v0, v0, v1
	v_xor_b32_e32 v1, 4, v227
	v_cmp_lt_i32_e64 s[6:7], v1, v2
	s_nop 1
	v_cndmask_b32_e64 v1, v227, v1, s[6:7]
	v_lshlrev_b32_e32 v1, 2, v1
	ds_bpermute_b32 v1, v1, v0
	s_mov_b32 s6, 0x800000
	s_waitcnt lgkmcnt(0)
	v_add_f32_e32 v0, v0, v1
	v_fmamk_f32 v0, v0, 0x3baaaaab, v191
	v_cmp_gt_f32_e64 s[6:7], s6, v0
	v_mul_f32_e32 v1, 0x4b800000, v0
	s_nop 0
	v_cndmask_b32_e64 v0, v0, v1, s[6:7]
	v_rsq_f32_e32 v0, v0
	s_nop 0
	v_mul_f32_e32 v1, 0x45800000, v0
	v_cndmask_b32_e64 v40, v0, v1, s[6:7]
	v_pk_mul_f32 v[20:21], v[20:21], v[40:41] op_sel_hi:[1,0]
	v_pk_mul_f32 v[22:23], v[22:23], v[40:41] op_sel_hi:[1,0]
	v_pk_mul_f32 v[16:17], v[16:17], v[40:41] op_sel_hi:[1,0]
	s_movk_i32 s6, 0x4000
	v_cmp_gt_i32_e64 s[6:7], s6, v59
	s_waitcnt vmcnt(0)
	v_pk_mul_f32 v[20:21], v[20:21], v[88:89]
	v_pk_mul_f32 v[28:29], v[22:23], v[90:91]
	v_pk_mul_f32 v[22:23], v[16:17], v[92:93]
	v_pk_mul_f32 v[16:17], v[18:19], v[40:41] op_sel_hi:[1,0]
	s_nop 0
	v_pk_mul_f32 v[16:17], v[16:17], v[94:95]
	s_and_saveexec_b64 s[12:13], s[6:7]
	s_cbranch_execz .LBB0_630
	ds_bpermute_b32 v18, v58, v20
	ds_bpermute_b32 v19, v58, v21
	s_waitcnt vmcnt(0)
	v_mov_b32_e32 v31, v70
	v_mov_b32_e32 v70, v69
	s_waitcnt lgkmcnt(0)
	v_pk_mul_f32 v[18:19], v[70:71], v[18:19]
	v_mov_b32_e32 v30, v68
	v_cndmask_b32_e64 v19, v19, -v19, s[2:3]
	v_cndmask_b32_e64 v18, v18, -v18, s[2:3]
	v_pk_fma_f32 v[20:21], v[20:21], v[30:31], v[18:19]
	ds_bpermute_b32 v18, v58, v28
	ds_bpermute_b32 v19, v58, v29
	v_mov_b32_e32 v31, v66
	v_mov_b32_e32 v66, v65
	v_mov_b32_e32 v30, v64
	s_waitcnt lgkmcnt(0)
	v_pk_mul_f32 v[18:19], v[66:67], v[18:19]
	s_nop 0
	v_cndmask_b32_e64 v19, v19, -v19, s[2:3]
	v_cndmask_b32_e64 v18, v18, -v18, s[2:3]
	v_pk_fma_f32 v[28:29], v[28:29], v[30:31], v[18:19]
	ds_bpermute_b32 v18, v58, v22
	ds_bpermute_b32 v19, v58, v23
	v_mov_b32_e32 v31, v62
	v_mov_b32_e32 v62, v61
	v_mov_b32_e32 v30, v60
	s_waitcnt lgkmcnt(0)
	v_pk_mul_f32 v[18:19], v[62:63], v[18:19]
	s_nop 0
	v_cndmask_b32_e64 v19, v19, -v19, s[2:3]
	v_cndmask_b32_e64 v18, v18, -v18, s[2:3]
	v_pk_fma_f32 v[22:23], v[22:23], v[30:31], v[18:19]
	ds_bpermute_b32 v18, v58, v16
	ds_bpermute_b32 v19, v58, v17
	v_mov_b32_e32 v31, v26
	v_mov_b32_e32 v26, v25
	v_mov_b32_e32 v30, v24
	s_waitcnt lgkmcnt(0)
	v_pk_mul_f32 v[18:19], v[26:27], v[18:19]
	s_nop 0
	v_cndmask_b32_e64 v19, v19, -v19, s[2:3]
	v_cndmask_b32_e64 v18, v18, -v18, s[2:3]
	v_pk_fma_f32 v[16:17], v[16:17], v[30:31], v[18:19]
	s_branch .LBB0_630
